# final RMSNorm pass: non-temporal hint on the read-once row loads
# baseline (speedup 1.0000x reference)
.LBB0_1999:
.LBB0_2000:
	s_cmp_lt_i32 s20, 17
	s_cselect_b64 s[4:5], -1, 0
	s_and_b64 s[2:3], s[4:5], s[2:3]
	s_andn2_b64 vcc, exec, s[2:3]
	s_cbranch_vccnz .LBB0_2004
	s_mov_b64 s[2:3], s[0:1]
	s_mov_b64 s[4:5], s[0:1]
	s_cmpk_gt_i32 s28, 0x7fff
	s_cbranch_scc1 .LBB0_2004
	s_load_dwordx2 s[6:7], s[0:1], 0x98
	s_load_dwordx2 s[8:9], s[2:3], 0xa0
	s_load_dwordx2 s[10:11], s[4:5], 0xa8
	s_ashr_i32 s29, s28, 31
	s_lshl_b64 s[0:1], s[28:29], 2
	v_lshlrev_b32_e32 v0, 4, v242
	v_mov_b32_e32 v1, 0
	s_waitcnt lgkmcnt(0)
	s_add_u32 s0, s10, s0
	s_addc_u32 s1, s11, s1
	s_add_u32 s0, s0, 0x100000
	s_addc_u32 s1, s1, 0
	s_ashr_i32 s31, s30, 31
	s_lshl_b64 s[2:3], s[30:31], 2
	s_lshl_b64 s[4:5], s[28:29], 12
	s_add_u32 s4, s8, s4
	s_addc_u32 s5, s9, s5
	v_lshl_add_u64 v[4:5], s[4:5], 0, v[0:1]
	s_mov_b64 s[4:5], 0x800
	v_lshl_add_u64 v[2:3], s[6:7], 0, v[0:1]
	v_lshl_add_u64 v[4:5], v[4:5], 0, s[4:5]
	s_lshl_b64 s[4:5], s[30:31], 12
	v_mov_b32_e32 v0, 0x358637bd
	global_load_dwordx4 v[20:23], v[2:3], off
	global_load_dwordx4 v[24:27], v[2:3], off offset:1024
	global_load_dwordx4 v[28:31], v[2:3], off offset:2048
	global_load_dwordx4 v[32:35], v[2:3], off offset:3072
	global_load_dword v18, v1, s[0:1]
	global_load_dwordx4 v[36:39], v[4:5], off offset:-2048 nt
	global_load_dwordx4 v[40:43], v[4:5], off offset:-1024 nt
	global_load_dwordx4 v[44:47], v[4:5], off nt
	global_load_dwordx4 v[48:51], v[4:5], off offset:1024 nt
.Lfin_A:
	v_lshl_add_u64 v[6:7], v[4:5], 0, s[4:5]
	s_add_i32 s28, s28, s30
	s_add_u32 s0, s0, s2
	s_addc_u32 s1, s1, s3
	s_cmp_lt_i32 s28, 0x8000
	s_cbranch_scc0 .Lfin_A_last
	global_load_dword v68, v1, s[0:1]
	global_load_dwordx4 v[52:55], v[6:7], off offset:-2048 nt
	global_load_dwordx4 v[56:59], v[6:7], off offset:-1024 nt
	global_load_dwordx4 v[60:63], v[6:7], off nt
	global_load_dwordx4 v[64:67], v[6:7], off offset:1024 nt
	s_waitcnt vmcnt(5)
	v_fmamk_f32 v18, v18, 0x3a800000, v0
	v_rsq_f32_e32 v18, v18
	s_nop 0
	v_pk_mul_f32 v[38:39], v[18:19], v[38:39] op_sel_hi:[0,1]
	v_pk_mul_f32 v[36:37], v[18:19], v[36:37] op_sel_hi:[0,1]
	v_pk_mul_f32 v[38:39], v[38:39], v[22:23]
	v_pk_mul_f32 v[36:37], v[36:37], v[20:21]
	global_store_dwordx4 v[4:5], v[36:39], off offset:-2048 nt
	v_pk_mul_f32 v[42:43], v[18:19], v[42:43] op_sel_hi:[0,1]
	v_pk_mul_f32 v[40:41], v[18:19], v[40:41] op_sel_hi:[0,1]
	v_pk_mul_f32 v[42:43], v[42:43], v[26:27]
	v_pk_mul_f32 v[40:41], v[40:41], v[24:25]
	global_store_dwordx4 v[4:5], v[40:43], off offset:-1024 nt
	v_pk_mul_f32 v[46:47], v[18:19], v[46:47] op_sel_hi:[0,1]
	v_pk_mul_f32 v[44:45], v[18:19], v[44:45] op_sel_hi:[0,1]
	v_pk_mul_f32 v[46:47], v[46:47], v[30:31]
	v_pk_mul_f32 v[44:45], v[44:45], v[28:29]
	global_store_dwordx4 v[4:5], v[44:47], off nt
	v_pk_mul_f32 v[50:51], v[18:19], v[50:51] op_sel_hi:[0,1]
	v_pk_mul_f32 v[48:49], v[18:19], v[48:49] op_sel_hi:[0,1]
	v_pk_mul_f32 v[50:51], v[50:51], v[34:35]
	v_pk_mul_f32 v[48:49], v[48:49], v[32:33]
	global_store_dwordx4 v[4:5], v[48:51], off offset:1024 nt
	v_lshl_add_u64 v[4:5], v[6:7], 0, s[4:5]
	s_add_i32 s28, s28, s30
	s_add_u32 s0, s0, s2
	s_addc_u32 s1, s1, s3
	s_cmp_lt_i32 s28, 0x8000
	s_cbranch_scc0 .Lfin_B_last
	global_load_dword v18, v1, s[0:1]
	global_load_dwordx4 v[36:39], v[4:5], off offset:-2048 nt
	global_load_dwordx4 v[40:43], v[4:5], off offset:-1024 nt
	global_load_dwordx4 v[44:47], v[4:5], off nt
	global_load_dwordx4 v[48:51], v[4:5], off offset:1024 nt
	s_waitcnt vmcnt(5)
	v_fmamk_f32 v68, v68, 0x3a800000, v0
	v_rsq_f32_e32 v68, v68
	s_nop 0
	v_pk_mul_f32 v[54:55], v[68:69], v[54:55] op_sel_hi:[0,1]
	v_pk_mul_f32 v[52:53], v[68:69], v[52:53] op_sel_hi:[0,1]
	v_pk_mul_f32 v[54:55], v[54:55], v[22:23]
	v_pk_mul_f32 v[52:53], v[52:53], v[20:21]
	global_store_dwordx4 v[6:7], v[52:55], off offset:-2048 nt
	v_pk_mul_f32 v[58:59], v[68:69], v[58:59] op_sel_hi:[0,1]
	v_pk_mul_f32 v[56:57], v[68:69], v[56:57] op_sel_hi:[0,1]
	v_pk_mul_f32 v[58:59], v[58:59], v[26:27]
	v_pk_mul_f32 v[56:57], v[56:57], v[24:25]
	global_store_dwordx4 v[6:7], v[56:59], off offset:-1024 nt
	v_pk_mul_f32 v[62:63], v[68:69], v[62:63] op_sel_hi:[0,1]
	v_pk_mul_f32 v[60:61], v[68:69], v[60:61] op_sel_hi:[0,1]
	v_pk_mul_f32 v[62:63], v[62:63], v[30:31]
	v_pk_mul_f32 v[60:61], v[60:61], v[28:29]
	global_store_dwordx4 v[6:7], v[60:63], off nt
	v_pk_mul_f32 v[66:67], v[68:69], v[66:67] op_sel_hi:[0,1]
	v_pk_mul_f32 v[64:65], v[68:69], v[64:65] op_sel_hi:[0,1]
	v_pk_mul_f32 v[66:67], v[66:67], v[34:35]
	v_pk_mul_f32 v[64:65], v[64:65], v[32:33]
	global_store_dwordx4 v[6:7], v[64:67], off offset:1024 nt
	s_branch .Lfin_A
